# sample-group HGRN recurrence units (phase-3 tail): the four per-step gate loads issued with the unit's load batch instead of one dependent round trip per step
# speedup vs baseline: 1.0186x; 1.0009x over previous
; DEV void hgrn_sample_unit(Frame& F, int b, int h) {
;     ...
;     { const int k = v, t = kq; const size_t g = (size_t)(T + b * 4 + t) * 512 + h * 128 + k; const float lbv = TB[TB_LB + h * 128 + k], oml = 1.0f - lbv;
;       const float z = HF[g]; Lf[t * 128 + k] = lbv + oml * __builtin_amdgcn_rcpf(1.0f + __expf(-z)); Lkk[t * 128 + k] = oml * __builtin_amdgcn_rcpf(1.0f + __expf(z)); Lqq[t * 128 + k] = bf2f(HQ[g]); }
;     float S[32];
;     const float* S0 = ((const float*)F.A.in[8]) + ((size_t)(b * 4 + h) * 128 + kq * 32) * 128 + v;
; #pragma unroll
;     for (int j = 0; j < 32; ++j) S[j] = S0[(size_t)j * 128];
;     __syncthreads();
;     for (int t = 0; t < 4; ++t) {
;         const float vt = bf2f(HI[(size_t)(T + b * 4 + t) * 512 + h * 128 + v]);
;         float o = 0.f;
; #pragma unroll
;         for (int j = 0; j < 32; ++j) { const int k = kq * 32 + j; S[j] = Lf[t * 128 + k] * S[j] + Lkk[t * 128 + k] * vt; o += Lqq[t * 128 + k] * S[j]; }
.LBB0_1672:
	s_or_b64 exec, exec, s[4:5]
	s_waitcnt lgkmcnt(0)
	s_barrier
	ds_read_b32 v18, v40
	s_mov_b64 s[4:5], -1
	s_waitcnt lgkmcnt(0)
	s_barrier
	v_cmp_lt_i32_e32 vcc, s26, v18
	v_readfirstlane_b32 s22, v18
	s_cbranch_vccnz .LBB0_1667
	s_and_b32 s4, s22, -4
	s_addk_i32 s4, 0x4000
	v_add_u32_e32 v18, s4, v1
	v_ashrrev_i32_e32 v19, 31, v18
	s_lshl_b32 s5, s22, 7
	v_lshlrev_b64 v[18:19], 9, v[18:19]
	s_and_b32 s24, s5, 0x180
	v_or_b32_e32 v18, s24, v18
	v_or_b32_e32 v18, v18, v2
	v_lshl_add_u64 v[20:21], v[18:19], 2, s[14:15]
	global_load_dword v29, v[20:21], off
	v_or_b32_e32 v20, s24, v2
	v_lshlrev_b32_e32 v20, 2, v20
	global_load_dword v41, v20, s[12:13]
	v_lshl_add_u64 v[18:19], v[18:19], 1, s[16:17]
	global_load_ushort v42, v[18:19], off
	s_ashr_i32 s23, s22, 31
	s_lshl_b64 s[22:23], s[22:23], 14
	v_lshl_add_u64 v[18:19], s[22:23], 0, v[6:7]
	v_lshl_add_u64 v[22:23], v[18:19], 2, v[8:9]
	v_add_co_u32_e32 v24, vcc, s28, v22
	global_load_dword v136, v[22:23], off
	global_load_dword v137, v[22:23], off offset:512
	global_load_dword v140, v[22:23], off offset:1024
	global_load_dword v141, v[22:23], off offset:1536
	global_load_dword v142, v[22:23], off offset:2048
	global_load_dword v143, v[22:23], off offset:2560
	global_load_dword v144, v[22:23], off offset:3072
	global_load_dword v145, v[22:23], off offset:3584
	v_addc_co_u32_e32 v25, vcc, 0, v23, vcc
	v_add_co_u32_e32 v30, vcc, s29, v22
	s_lshl_b32 s18, s24, 1
	s_nop 0
	v_addc_co_u32_e32 v31, vcc, 0, v23, vcc
	v_add_co_u32_e32 v34, vcc, s30, v22
	s_ashr_i32 s5, s4, 31
	s_nop 0
	v_addc_co_u32_e32 v35, vcc, 0, v23, vcc
	global_load_dword v146, v[30:31], off
	global_load_dword v147, v[30:31], off offset:512
	global_load_dword v148, v[30:31], off offset:1024
	global_load_dword v149, v[30:31], off offset:1536
	global_load_dword v22, v[30:31], off offset:2048
	global_load_dword v23, v[30:31], off offset:2560
	global_load_dword v26, v[30:31], off offset:3072
	global_load_dword v27, v[30:31], off offset:3584
	global_load_dword v150, v[24:25], off offset:512
	global_load_dword v151, v[24:25], off offset:1024
	global_load_dword v152, v[24:25], off offset:1536
	global_load_dword v153, v[24:25], off offset:2048
	global_load_dword v154, v[24:25], off offset:2560
	global_load_dword v155, v[24:25], off offset:3072
	s_nop 0
	global_load_dword v25, v[24:25], off offset:3584
	s_nop 0
	global_load_dword v28, v[34:35], off
	v_lshl_add_u64 v[20:21], v[10:11], 0, s[18:19]
	s_lshl_b64 s[22:23], s[4:5], 10
	v_lshl_add_u64 v[36:37], v[20:21], 0, s[22:23]
	global_load_ushort v240, v[36:37], off
	global_load_ushort v241, v[36:37], off offset:1024
	global_load_ushort v242, v[36:37], off offset:2048
	global_load_ushort v243, v[36:37], off offset:3072
	s_waitcnt vmcnt(30)
	v_mul_f32_e32 v24, 0xbfb8aa3b, v29
	v_mul_f32_e32 v29, 0x3fb8aa3b, v29
	v_exp_f32_e32 v24, v24
	v_exp_f32_e32 v43, v29
	global_load_dword v156, v[30:31], off offset:-4096
	global_load_dword v29, v[34:35], off offset:512
	s_nop 0
	global_load_dword v30, v[34:35], off offset:1024
	global_load_dword v31, v[34:35], off offset:1536
	global_load_dword v32, v[34:35], off offset:2048
	global_load_dword v33, v[34:35], off offset:2560
	global_load_dword v134, v[34:35], off offset:3072
	global_load_dword v135, v[34:35], off offset:3584
	s_waitcnt vmcnt(37)
	v_sub_f32_e32 v34, 1.0, v41
	v_add_f32_e32 v24, 1.0, v24
	v_add_f32_e32 v35, 1.0, v43
	v_rcp_f32_e32 v24, v24
	v_rcp_f32_e32 v35, v35
	s_waitcnt vmcnt(36)
	v_lshlrev_b32_e32 v42, 16, v42
	ds_write_b32 v160, v42 offset:4096
	v_fmac_f32_e32 v41, v34, v24
	v_mul_f32_e32 v24, v34, v35
	ds_write2st64_b32 v160, v41, v24 offset1:8
	s_waitcnt lgkmcnt(0)
	s_barrier
	ds_read_b128 v[58:61], v4
	ds_read_b128 v[62:65], v4 offset:16
	ds_read_b128 v[66:69], v4 offset:32
	ds_read_b128 v[70:73], v4 offset:48
	ds_read_b128 v[34:37], v4 offset:2048
	ds_read_b128 v[42:45], v4 offset:2064
	ds_read_b128 v[74:77], v4 offset:4096
	ds_read_b128 v[78:81], v4 offset:4112
	ds_read_b128 v[46:49], v4 offset:2080
	ds_read_b128 v[50:53], v4 offset:2096
	ds_read_b128 v[82:85], v4 offset:4128
	ds_read_b128 v[86:89], v4 offset:4144
	ds_read_b128 v[90:93], v4 offset:4160
	ds_read_b128 v[94:97], v4 offset:4176
	ds_read_b128 v[98:101], v4 offset:64
	ds_read_b128 v[102:105], v4 offset:80
	ds_read_b128 v[54:57], v4 offset:2112
	ds_read_b128 v[106:109], v4 offset:2128
	ds_read_b128 v[110:113], v4 offset:4192
	ds_read_b128 v[114:117], v4 offset:4208
	ds_read_b128 v[118:121], v4 offset:96
	ds_read_b128 v[122:125], v4 offset:112
	ds_read_b128 v[126:129], v4 offset:2144
	ds_read_b128 v[130:133], v4 offset:2160
	s_waitcnt vmcnt(0)
	v_lshlrev_b32_e32 v24, 16, v240
	s_waitcnt lgkmcnt(14)
	v_mul_f32_e32 v34, v34, v24
	v_mul_f32_e32 v35, v35, v24
	v_fmac_f32_e32 v34, v136, v58
	v_mul_f32_e32 v36, v36, v24
	v_mul_f32_e32 v41, v42, v24
	v_mul_f32_e32 v42, v43, v24
	v_mul_f32_e32 v43, v44, v24
	v_mul_f32_e32 v44, v45, v24
	v_mul_f32_e32 v45, v46, v24
	v_mul_f32_e32 v46, v47, v24
	v_mul_f32_e32 v47, v48, v24
	v_mul_f32_e32 v48, v49, v24
	v_mul_f32_e32 v49, v50, v24
	v_mul_f32_e32 v50, v51, v24
	v_mul_f32_e32 v51, v52, v24
	v_mul_f32_e32 v52, v53, v24
	s_waitcnt lgkmcnt(7)
; DEV void hgrn_sample_unit(Frame& F, int b, int h) {
;     ...
;     for (int t = 0; t < 4; ++t) {
;         const float vt = bf2f(HI[(size_t)(T + b * 4 + t) * 512 + h * 128 + v]);
;         float o = 0.f;
; #pragma unroll
;         for (int j = 0; j < 32; ++j) { const int k = kq * 32 + j; S[j] = Lf[t * 128 + k] * S[j] + Lkk[t * 128 + k] * vt; o += Lqq[t * 128 + k] * S[j]; }
;         Lo[kq * 128 + v] = o;
;         __syncthreads();
;         if (kq == 0) Lot[t * 128 + v] = (Lo[v] + Lo[128 + v]) + (Lo[256 + v] + Lo[384 + v]);
;         __syncthreads();
	v_mul_f32_e32 v53, v54, v24
	v_mul_f32_e32 v54, v55, v24
	v_mul_f32_e32 v55, v56, v24
	v_mul_f32_e32 v56, v57, v24
	v_fmac_f32_e32 v35, v137, v59
	v_fma_f32 v57, v74, v34, 0
	v_mul_f32_e32 v37, v37, v24
	v_fmac_f32_e32 v36, v140, v60
	v_fmac_f32_e32 v57, v75, v35
	v_fmac_f32_e32 v37, v141, v61
	v_fmac_f32_e32 v57, v76, v36
	v_fmac_f32_e32 v41, v142, v62
	v_fmac_f32_e32 v57, v77, v37
	v_fmac_f32_e32 v42, v143, v63
	v_fmac_f32_e32 v57, v78, v41
	v_fmac_f32_e32 v43, v144, v64
	v_fmac_f32_e32 v57, v79, v42
	v_fmac_f32_e32 v44, v145, v65
	v_fmac_f32_e32 v57, v80, v43
	v_fmac_f32_e32 v45, v156, v66
	v_fmac_f32_e32 v57, v81, v44
	v_fmac_f32_e32 v46, v150, v67
	v_fmac_f32_e32 v57, v82, v45
	v_fmac_f32_e32 v47, v151, v68
	v_fmac_f32_e32 v57, v83, v46
	v_fmac_f32_e32 v48, v152, v69
	v_fmac_f32_e32 v57, v84, v47
	v_fmac_f32_e32 v49, v153, v70
	v_fmac_f32_e32 v57, v85, v48
	v_fmac_f32_e32 v50, v154, v71
	v_fmac_f32_e32 v57, v86, v49
	v_fmac_f32_e32 v51, v155, v72
	v_fmac_f32_e32 v57, v87, v50
	v_fmac_f32_e32 v52, v25, v73
	v_fmac_f32_e32 v57, v88, v51
	v_fmac_f32_e32 v53, v146, v98
	v_fmac_f32_e32 v57, v89, v52
	v_fmac_f32_e32 v54, v147, v99
	v_fmac_f32_e32 v57, v90, v53
	v_fmac_f32_e32 v55, v148, v100
	v_fmac_f32_e32 v57, v91, v54
	s_waitcnt lgkmcnt(6)
	v_pk_mul_f32 v[106:107], v[106:107], v[24:25] op_sel_hi:[1,0]
	v_fmac_f32_e32 v56, v149, v101
	v_fmac_f32_e32 v57, v92, v55
	v_pk_mul_f32 v[108:109], v[108:109], v[24:25] op_sel_hi:[1,0]
	s_waitcnt lgkmcnt(1)
	v_pk_mul_f32 v[126:127], v[126:127], v[24:25] op_sel_hi:[1,0]
	v_pk_mul_f32 v[128:129], v[128:129], v[24:25] op_sel_hi:[1,0]
	s_waitcnt lgkmcnt(0)
	v_pk_mul_f32 v[130:131], v[130:131], v[24:25] op_sel_hi:[1,0]
	v_pk_mul_f32 v[132:133], v[132:133], v[24:25] op_sel_hi:[1,0]
	v_pk_fma_f32 v[24:25], v[22:23], v[102:103], v[106:107]
	v_fmac_f32_e32 v57, v93, v56
	v_fmac_f32_e32 v57, v94, v24
	v_pk_fma_f32 v[26:27], v[26:27], v[104:105], v[108:109]
	v_fmac_f32_e32 v57, v95, v25
	v_fmac_f32_e32 v57, v96, v26
	v_pk_fma_f32 v[28:29], v[28:29], v[118:119], v[126:127]
	v_fmac_f32_e32 v57, v97, v27
	v_fmac_f32_e32 v57, v110, v28
	v_pk_fma_f32 v[30:31], v[30:31], v[120:121], v[128:129]
	v_fmac_f32_e32 v57, v111, v29
	v_fmac_f32_e32 v57, v112, v30
	v_pk_fma_f32 v[32:33], v[32:33], v[122:123], v[130:131]
	v_fmac_f32_e32 v57, v113, v31
	v_fmac_f32_e32 v57, v114, v32
	v_pk_fma_f32 v[22:23], v[134:135], v[124:125], v[132:133]
	v_fmac_f32_e32 v57, v115, v33
	v_fmac_f32_e32 v57, v116, v22
	v_fmac_f32_e32 v57, v117, v23
	ds_write_b32 v160, v57 offset:6144
	s_waitcnt lgkmcnt(0)
	s_barrier
	s_and_saveexec_b64 s[22:23], s[2:3]
	s_cbranch_execz .LBB0_1675
	ds_read2st64_b32 v[58:59], v160 offset0:26 offset1:28
	ds_read_b32 v60, v3 offset:6144
	ds_read_b32 v61, v160 offset:7680
	s_waitcnt lgkmcnt(0)
	v_pk_add_f32 v[58:59], v[58:59], v[60:61]
	s_nop 0
	v_add_f32_e32 v57, v58, v59
	ds_write_b32 v160, v57 offset:8192
.LBB0_1675:
	s_or_b64 exec, exec, s[22:23]
	s_or_b32 s22, s4, 1
	s_ashr_i32 s23, s22, 31
	s_lshl_b64 s[22:23], s[22:23], 10
	v_lshl_add_u64 v[58:59], v[20:21], 0, s[22:23]
	s_waitcnt lgkmcnt(0)
	s_barrier
	ds_read_b128 v[78:81], v4 offset:512
	ds_read_b128 v[82:85], v4 offset:528
	ds_read_b128 v[86:89], v4 offset:544
	ds_read_b128 v[90:93], v4 offset:560
	ds_read_b128 v[58:61], v4 offset:2560
	ds_read_b128 v[62:65], v4 offset:2576
	ds_read_b128 v[94:97], v4 offset:4608
	ds_read_b128 v[98:101], v4 offset:4624
	ds_read_b128 v[66:69], v4 offset:2592
	ds_read_b128 v[70:73], v4 offset:2608
	ds_read_b128 v[102:105], v4 offset:4640
	ds_read_b128 v[106:109], v4 offset:4656
	ds_read_b128 v[110:113], v4 offset:576
	ds_read_b128 v[114:117], v4 offset:592
	ds_read_b128 v[74:77], v4 offset:2624
	ds_read_b128 v[118:121], v4 offset:2640
	ds_read_b128 v[122:125], v4 offset:4672
	ds_read_b128 v[126:129], v4 offset:4688
	ds_read_b128 v[130:133], v4 offset:608
	ds_read_b128 v[134:137], v4 offset:624
	ds_read_b128 v[140:143], v4 offset:2656
	ds_read_b128 v[144:147], v4 offset:2672
	ds_read_b128 v[148:151], v4 offset:4704
	ds_read_b128 v[152:155], v4 offset:4720
	s_waitcnt vmcnt(0)
	v_lshlrev_b32_e32 v156, 16, v241
	s_waitcnt lgkmcnt(14)
	v_mul_f32_e32 v57, v58, v156
	v_mul_f32_e32 v58, v59, v156
	v_mul_f32_e32 v59, v60, v156
	v_mul_f32_e32 v60, v61, v156
	v_mul_f32_e32 v61, v62, v156
	v_fmac_f32_e32 v57, v34, v78
	v_fmac_f32_e32 v58, v35, v79
	v_fmac_f32_e32 v61, v41, v82
	v_fma_f32 v41, v94, v57, 0
	v_fmac_f32_e32 v59, v36, v80
	v_fmac_f32_e32 v41, v95, v58
	v_fmac_f32_e32 v60, v37, v81
	v_fmac_f32_e32 v41, v96, v59
	v_mul_f32_e32 v62, v63, v156
	v_fmac_f32_e32 v41, v97, v60
	v_mul_f32_e32 v63, v64, v156
	v_fmac_f32_e32 v62, v42, v83
	v_fmac_f32_e32 v41, v98, v61
	v_mul_f32_e32 v64, v65, v156
	v_fmac_f32_e32 v63, v43, v84
	v_fmac_f32_e32 v41, v99, v62
	v_mul_f32_e32 v65, v66, v156
	v_fmac_f32_e32 v64, v44, v85
	v_fmac_f32_e32 v41, v100, v63
	v_mul_f32_e32 v66, v67, v156
	v_fmac_f32_e32 v65, v45, v86
	v_fmac_f32_e32 v41, v101, v64
	v_mul_f32_e32 v67, v68, v156
	v_fmac_f32_e32 v66, v46, v87
	s_waitcnt lgkmcnt(13)
	v_fmac_f32_e32 v41, v102, v65
	v_mul_f32_e32 v68, v69, v156
	v_fmac_f32_e32 v67, v47, v88
	v_fmac_f32_e32 v41, v103, v66
	v_mul_f32_e32 v69, v70, v156
	v_fmac_f32_e32 v68, v48, v89
	v_fmac_f32_e32 v41, v104, v67
	v_mul_f32_e32 v70, v71, v156
	v_fmac_f32_e32 v69, v49, v90
	v_fmac_f32_e32 v41, v105, v68
	v_mul_f32_e32 v71, v72, v156
	v_fmac_f32_e32 v70, v50, v91
	s_waitcnt lgkmcnt(12)
	v_fmac_f32_e32 v41, v106, v69
	v_mul_f32_e32 v72, v73, v156
	v_fmac_f32_e32 v71, v51, v92
	v_fmac_f32_e32 v41, v107, v70
	s_waitcnt lgkmcnt(9)
; DEV void hgrn_sample_unit(Frame& F, int b, int h) {
;     ...
;     for (int t = 0; t < 4; ++t) {
;         const float vt = bf2f(HI[(size_t)(T + b * 4 + t) * 512 + h * 128 + v]);
;         float o = 0.f;
; #pragma unroll
;         for (int j = 0; j < 32; ++j) { const int k = kq * 32 + j; S[j] = Lf[t * 128 + k] * S[j] + Lkk[t * 128 + k] * vt; o += Lqq[t * 128 + k] * S[j]; }
;         Lo[kq * 128 + v] = o;
;         __syncthreads();
;         if (kq == 0) Lot[t * 128 + v] = (Lo[v] + Lo[128 + v]) + (Lo[256 + v] + Lo[384 + v]);
;         __syncthreads();
	v_mul_f32_e32 v73, v74, v156
	v_fmac_f32_e32 v72, v52, v93
	v_fmac_f32_e32 v41, v108, v71
	v_mul_f32_e32 v74, v75, v156
	v_fmac_f32_e32 v73, v53, v110
	v_fmac_f32_e32 v41, v109, v72
	v_mul_f32_e32 v75, v76, v156
	v_fmac_f32_e32 v74, v54, v111
	s_waitcnt lgkmcnt(7)
	v_fmac_f32_e32 v41, v122, v73
	v_mul_f32_e32 v76, v77, v156
	v_pk_mul_f32 v[118:119], v[118:119], v[156:157] op_sel_hi:[1,0]
	v_fmac_f32_e32 v75, v55, v112
	v_fmac_f32_e32 v41, v123, v74
	v_fmac_f32_e32 v76, v56, v113
	v_pk_fma_f32 v[24:25], v[24:25], v[114:115], v[118:119]
	v_fmac_f32_e32 v41, v124, v75
	v_pk_mul_f32 v[120:121], v[120:121], v[156:157] op_sel_hi:[1,0]
	s_waitcnt lgkmcnt(6)
	v_pk_mul_f32 v[34:35], v[126:127], v[24:25]
	v_fmac_f32_e32 v41, v125, v76
	v_pk_fma_f32 v[26:27], v[26:27], v[116:117], v[120:121]
	v_add_f32_e32 v34, v41, v34
	s_waitcnt lgkmcnt(3)
	v_pk_mul_f32 v[140:141], v[140:141], v[156:157] op_sel_hi:[1,0]
	v_pk_mul_f32 v[36:37], v[128:129], v[26:27]
	v_add_f32_e32 v34, v34, v35
	v_pk_fma_f32 v[28:29], v[28:29], v[130:131], v[140:141]
	v_add_f32_e32 v34, v34, v36
	v_pk_mul_f32 v[142:143], v[142:143], v[156:157] op_sel_hi:[1,0]
	s_waitcnt lgkmcnt(1)
	v_pk_mul_f32 v[42:43], v[148:149], v[28:29]
	v_add_f32_e32 v34, v34, v37
	v_pk_fma_f32 v[30:31], v[30:31], v[132:133], v[142:143]
	v_add_f32_e32 v34, v34, v42
	v_pk_mul_f32 v[144:145], v[144:145], v[156:157] op_sel_hi:[1,0]
	v_pk_mul_f32 v[44:45], v[150:151], v[30:31]
	v_add_f32_e32 v34, v34, v43
	v_pk_fma_f32 v[32:33], v[32:33], v[134:135], v[144:145]
	v_add_f32_e32 v34, v34, v44
	v_add_f32_e32 v36, v34, v45
	s_waitcnt lgkmcnt(0)
	v_pk_mul_f32 v[34:35], v[152:153], v[32:33]
	s_nop 0
	v_add_f32_e32 v34, v36, v34
	v_add_f32_e32 v36, v34, v35
	v_pk_mul_f32 v[34:35], v[146:147], v[156:157] op_sel_hi:[1,0]
	s_nop 0
	v_pk_fma_f32 v[22:23], v[22:23], v[136:137], v[34:35]
	s_nop 0
	v_pk_mul_f32 v[34:35], v[154:155], v[22:23]
	s_nop 0
	v_add_f32_e32 v34, v36, v34
	v_add_f32_e32 v34, v34, v35
	ds_write_b32 v160, v34 offset:6144
	s_waitcnt lgkmcnt(0)
	s_barrier
	s_and_saveexec_b64 s[22:23], s[2:3]
	s_cbranch_execz .LBB0_1677
	ds_read2st64_b32 v[34:35], v160 offset0:26 offset1:28
	ds_read_b32 v36, v3 offset:6144
	ds_read_b32 v37, v160 offset:7680
	s_waitcnt lgkmcnt(0)
	v_pk_add_f32 v[34:35], v[34:35], v[36:37]
	s_nop 0
	v_add_f32_e32 v34, v34, v35
	ds_write_b32 v160, v34 offset:8704
.LBB0_1677:
	s_or_b64 exec, exec, s[22:23]
	s_or_b32 s22, s4, 2
	s_ashr_i32 s23, s22, 31
	s_lshl_b64 s[22:23], s[22:23], 10
	v_lshl_add_u64 v[34:35], v[20:21], 0, s[22:23]
	s_waitcnt lgkmcnt(0)
	s_barrier
	ds_read_b128 v[78:81], v4 offset:1024
	ds_read_b128 v[82:85], v4 offset:1040
	ds_read_b128 v[86:89], v4 offset:1056
	ds_read_b128 v[90:93], v4 offset:1072
	ds_read_b128 v[34:37], v4 offset:3072
	ds_read_b128 v[42:45], v4 offset:3088
	ds_read_b128 v[94:97], v4 offset:5120
	ds_read_b128 v[98:101], v4 offset:5136
	ds_read_b128 v[46:49], v4 offset:3104
	ds_read_b128 v[50:53], v4 offset:3120
	ds_read_b128 v[102:105], v4 offset:5152
	ds_read_b128 v[106:109], v4 offset:5168
	ds_read_b128 v[110:113], v4 offset:1088
	ds_read_b128 v[114:117], v4 offset:1104
	ds_read_b128 v[118:121], v4 offset:3136
	ds_read_b128 v[122:125], v4 offset:3152
	ds_read_b128 v[126:129], v4 offset:5184
	ds_read_b128 v[130:133], v4 offset:5200
	ds_read_b128 v[134:137], v4 offset:1120
	ds_read_b128 v[140:143], v4 offset:1136
	ds_read_b128 v[144:147], v4 offset:3168
	ds_read_b128 v[148:151], v4 offset:3184
	ds_read_b128 v[152:155], v4 offset:5216
	ds_read_b128 v[162:165], v4 offset:5232
	s_waitcnt vmcnt(0)
	v_lshlrev_b32_e32 v156, 16, v242
	s_waitcnt lgkmcnt(14)
	v_mul_f32_e32 v34, v34, v156
	v_mul_f32_e32 v35, v35, v156
	v_fmac_f32_e32 v34, v57, v78
	v_mul_f32_e32 v36, v36, v156
	v_fmac_f32_e32 v35, v58, v79
	v_fma_f32 v57, v94, v34, 0
	v_mul_f32_e32 v37, v37, v156
	v_fmac_f32_e32 v36, v59, v80
	v_fmac_f32_e32 v57, v95, v35
	v_mul_f32_e32 v41, v42, v156
	v_fmac_f32_e32 v37, v60, v81
	v_fmac_f32_e32 v57, v96, v36
	v_mul_f32_e32 v42, v43, v156
	v_fmac_f32_e32 v41, v61, v82
	v_fmac_f32_e32 v57, v97, v37
	v_mul_f32_e32 v43, v44, v156
	v_fmac_f32_e32 v42, v62, v83
	v_fmac_f32_e32 v57, v98, v41
	v_mul_f32_e32 v44, v45, v156
	v_fmac_f32_e32 v43, v63, v84
	v_fmac_f32_e32 v57, v99, v42
	v_mul_f32_e32 v45, v46, v156
	v_fmac_f32_e32 v44, v64, v85
	v_fmac_f32_e32 v57, v100, v43
	v_mul_f32_e32 v46, v47, v156
	v_fmac_f32_e32 v45, v65, v86
	v_fmac_f32_e32 v57, v101, v44
	v_mul_f32_e32 v47, v48, v156
	v_fmac_f32_e32 v46, v66, v87
	s_waitcnt lgkmcnt(13)
	v_fmac_f32_e32 v57, v102, v45
	v_mul_f32_e32 v48, v49, v156
	v_fmac_f32_e32 v47, v67, v88
	v_fmac_f32_e32 v57, v103, v46
	v_mul_f32_e32 v49, v50, v156
	v_fmac_f32_e32 v48, v68, v89
	v_fmac_f32_e32 v57, v104, v47
	v_mul_f32_e32 v50, v51, v156
	v_fmac_f32_e32 v49, v69, v90
	v_fmac_f32_e32 v57, v105, v48
	v_mul_f32_e32 v51, v52, v156
	v_fmac_f32_e32 v50, v70, v91
	s_waitcnt lgkmcnt(12)
	v_fmac_f32_e32 v57, v106, v49
	v_mul_f32_e32 v52, v53, v156
	v_fmac_f32_e32 v51, v71, v92
	v_fmac_f32_e32 v57, v107, v50
	s_waitcnt lgkmcnt(9)
	v_mul_f32_e32 v53, v118, v156
	v_fmac_f32_e32 v52, v72, v93
	v_fmac_f32_e32 v57, v108, v51
	v_mul_f32_e32 v54, v119, v156
	v_fmac_f32_e32 v53, v73, v110
	v_fmac_f32_e32 v57, v109, v52
	v_mul_f32_e32 v55, v120, v156
	v_fmac_f32_e32 v54, v74, v111
	s_waitcnt lgkmcnt(7)
	v_fmac_f32_e32 v57, v126, v53
	v_mul_f32_e32 v56, v121, v156
	v_pk_mul_f32 v[118:119], v[122:123], v[156:157] op_sel_hi:[1,0]
	v_fmac_f32_e32 v55, v75, v112
	v_fmac_f32_e32 v57, v127, v54
	v_fmac_f32_e32 v56, v76, v113
	v_pk_fma_f32 v[24:25], v[24:25], v[114:115], v[118:119]
	v_fmac_f32_e32 v57, v128, v55
	v_pk_mul_f32 v[120:121], v[124:125], v[156:157] op_sel_hi:[1,0]
	s_waitcnt lgkmcnt(6)
	v_pk_mul_f32 v[58:59], v[130:131], v[24:25]
	v_fmac_f32_e32 v57, v129, v56
	v_pk_fma_f32 v[26:27], v[26:27], v[116:117], v[120:121]
	v_add_f32_e32 v57, v57, v58
	s_waitcnt lgkmcnt(3)
	v_pk_mul_f32 v[122:123], v[144:145], v[156:157] op_sel_hi:[1,0]
	v_pk_mul_f32 v[60:61], v[132:133], v[26:27]
	v_add_f32_e32 v57, v57, v59
	v_pk_fma_f32 v[28:29], v[28:29], v[134:135], v[122:123]
	v_add_f32_e32 v57, v57, v60
	v_pk_mul_f32 v[124:125], v[146:147], v[156:157] op_sel_hi:[1,0]
	s_waitcnt lgkmcnt(1)
	v_pk_mul_f32 v[62:63], v[152:153], v[28:29]
	v_add_f32_e32 v57, v57, v61
	v_pk_fma_f32 v[30:31], v[30:31], v[136:137], v[124:125]
	v_add_f32_e32 v57, v57, v62
	v_pk_mul_f32 v[144:145], v[148:149], v[156:157] op_sel_hi:[1,0]
	v_pk_mul_f32 v[64:65], v[154:155], v[30:31]
	v_add_f32_e32 v57, v57, v63
	v_pk_fma_f32 v[32:33], v[32:33], v[140:141], v[144:145]
	v_add_f32_e32 v57, v57, v64
	v_add_f32_e32 v57, v57, v65
	s_waitcnt lgkmcnt(0)
	v_pk_mul_f32 v[58:59], v[162:163], v[32:33]
	s_nop 0
	v_add_f32_e32 v57, v57, v58
	v_add_f32_e32 v57, v57, v59
	v_pk_mul_f32 v[58:59], v[150:151], v[156:157] op_sel_hi:[1,0]
	s_nop 0
	v_pk_fma_f32 v[22:23], v[22:23], v[142:143], v[58:59]
	s_nop 0
	v_pk_mul_f32 v[58:59], v[164:165], v[22:23]
	s_nop 0
	v_add_f32_e32 v57, v57, v58
	v_add_f32_e32 v57, v57, v59
	ds_write_b32 v160, v57 offset:6144
	s_waitcnt lgkmcnt(0)
	s_barrier
; DEV void hgrn_sample_unit(Frame& F, int b, int h) {
;     ...
;     for (int t = 0; t < 4; ++t) {
;         const float vt = bf2f(HI[(size_t)(T + b * 4 + t) * 512 + h * 128 + v]);
;         float o = 0.f;
; #pragma unroll
;         for (int j = 0; j < 32; ++j) { const int k = kq * 32 + j; S[j] = Lf[t * 128 + k] * S[j] + Lkk[t * 128 + k] * vt; o += Lqq[t * 128 + k] * S[j]; }
;         Lo[kq * 128 + v] = o;
;         __syncthreads();
;         if (kq == 0) Lot[t * 128 + v] = (Lo[v] + Lo[128 + v]) + (Lo[256 + v] + Lo[384 + v]);
;         __syncthreads();
	s_and_saveexec_b64 s[22:23], s[2:3]
	s_cbranch_execz .LBB0_1679
	ds_read2st64_b32 v[58:59], v160 offset0:26 offset1:28
	ds_read_b32 v60, v3 offset:6144
	ds_read_b32 v61, v160 offset:7680
	s_waitcnt lgkmcnt(0)
	v_pk_add_f32 v[58:59], v[58:59], v[60:61]
	s_nop 0
	v_add_f32_e32 v57, v58, v59
	ds_write_b32 v160, v57 offset:9216
.LBB0_1679:
	s_or_b64 exec, exec, s[22:23]
	s_or_b32 s22, s4, 3
	s_ashr_i32 s23, s22, 31
	s_lshl_b64 s[22:23], s[22:23], 10
	v_lshl_add_u64 v[20:21], v[20:21], 0, s[22:23]
	s_waitcnt lgkmcnt(0)
	s_barrier
	ds_read_b128 v[78:81], v4 offset:1536
	ds_read_b128 v[82:85], v4 offset:1552
	ds_read_b128 v[86:89], v4 offset:1568
	ds_read_b128 v[90:93], v4 offset:1584
	ds_read_b128 v[58:61], v4 offset:3584
	ds_read_b128 v[62:65], v4 offset:3600
	ds_read_b128 v[94:97], v4 offset:5632
	ds_read_b128 v[98:101], v4 offset:5648
	ds_read_b128 v[102:105], v4 offset:3616
	ds_read_b128 v[106:109], v4 offset:3632
	ds_read_b128 v[110:113], v4 offset:5664
	ds_read_b128 v[114:117], v4 offset:5680
	ds_read_b128 v[118:121], v4 offset:1600
	ds_read_b128 v[122:125], v4 offset:1616
	ds_read_b128 v[126:129], v4 offset:3648
	ds_read_b128 v[130:133], v4 offset:3664
	ds_read_b128 v[134:137], v4 offset:5696
	ds_read_b128 v[140:143], v4 offset:5712
	ds_read_b128 v[144:147], v4 offset:1632
	ds_read_b128 v[148:151], v4 offset:1648
	ds_read_b128 v[152:155], v4 offset:3680
	ds_read_b128 v[162:165], v4 offset:3696
	ds_read_b128 v[166:169], v4 offset:5728
	ds_read_b128 v[170:173], v4 offset:5744
	s_waitcnt vmcnt(0)
	v_lshlrev_b32_e32 v156, 16, v243
	s_waitcnt lgkmcnt(14)
	v_mul_f32_e32 v69, v58, v156
	v_mul_f32_e32 v70, v59, v156
	v_mul_f32_e32 v73, v62, v156
	v_fmac_f32_e32 v69, v34, v78
	v_mul_f32_e32 v71, v60, v156
	v_fmac_f32_e32 v70, v35, v79
	v_fmac_f32_e32 v73, v41, v82
	v_fma_f32 v41, v94, v69, 0
	v_mul_f32_e32 v72, v61, v156
	v_fmac_f32_e32 v71, v36, v80
	v_fmac_f32_e32 v41, v95, v70
	v_fmac_f32_e32 v72, v37, v81
	v_fmac_f32_e32 v41, v96, v71
	v_mul_f32_e32 v74, v63, v156
	v_fmac_f32_e32 v41, v97, v72
	v_mul_f32_e32 v75, v64, v156
	v_fmac_f32_e32 v74, v42, v83
	v_fmac_f32_e32 v41, v98, v73
	v_mul_f32_e32 v76, v65, v156
	v_fmac_f32_e32 v75, v43, v84
	v_fmac_f32_e32 v41, v99, v74
	v_mul_f32_e32 v61, v102, v156
	v_fmac_f32_e32 v76, v44, v85
	v_fmac_f32_e32 v41, v100, v75
	v_mul_f32_e32 v62, v103, v156
	v_fmac_f32_e32 v61, v45, v86
	v_fmac_f32_e32 v41, v101, v76
	v_mul_f32_e32 v63, v104, v156
	v_fmac_f32_e32 v62, v46, v87
	s_waitcnt lgkmcnt(13)
	v_fmac_f32_e32 v41, v110, v61
	v_mul_f32_e32 v64, v105, v156
	v_fmac_f32_e32 v63, v47, v88
	v_fmac_f32_e32 v41, v111, v62
	v_mul_f32_e32 v65, v106, v156
	v_fmac_f32_e32 v64, v48, v89
	v_fmac_f32_e32 v41, v112, v63
	v_mul_f32_e32 v66, v107, v156
	v_fmac_f32_e32 v65, v49, v90
	v_fmac_f32_e32 v41, v113, v64
	v_mul_f32_e32 v67, v108, v156
	v_fmac_f32_e32 v66, v50, v91
	s_waitcnt lgkmcnt(12)
	v_fmac_f32_e32 v41, v114, v65
	v_mul_f32_e32 v68, v109, v156
	v_fmac_f32_e32 v67, v51, v92
	v_fmac_f32_e32 v41, v115, v66
	s_waitcnt lgkmcnt(9)
	v_mul_f32_e32 v57, v126, v156
	v_fmac_f32_e32 v68, v52, v93
	v_fmac_f32_e32 v41, v116, v67
	v_mul_f32_e32 v58, v127, v156
	v_fmac_f32_e32 v57, v53, v118
	v_fmac_f32_e32 v41, v117, v68
	v_mul_f32_e32 v59, v128, v156
	v_fmac_f32_e32 v58, v54, v119
	s_waitcnt lgkmcnt(7)
	v_fmac_f32_e32 v41, v134, v57
	v_mul_f32_e32 v60, v129, v156
	v_pk_mul_f32 v[20:21], v[130:131], v[156:157] op_sel_hi:[1,0]
	v_fmac_f32_e32 v59, v55, v120
	v_fmac_f32_e32 v41, v135, v58
	v_pk_mul_f32 v[102:103], v[132:133], v[156:157] op_sel_hi:[1,0]
	s_waitcnt lgkmcnt(3)
	v_pk_mul_f32 v[104:105], v[152:153], v[156:157] op_sel_hi:[1,0]
	v_fmac_f32_e32 v60, v56, v121
	v_pk_fma_f32 v[36:37], v[24:25], v[122:123], v[20:21]
	v_fmac_f32_e32 v41, v136, v59
	v_pk_fma_f32 v[34:35], v[26:27], v[124:125], v[102:103]
	v_pk_fma_f32 v[26:27], v[28:29], v[144:145], v[104:105]
	v_pk_mul_f32 v[28:29], v[140:141], v[36:37]
	v_fmac_f32_e32 v41, v137, v60
	v_pk_mul_f32 v[106:107], v[154:155], v[156:157] op_sel_hi:[1,0]
	v_add_f32_e32 v28, v41, v28
	v_pk_fma_f32 v[24:25], v[30:31], v[146:147], v[106:107]
	v_pk_mul_f32 v[30:31], v[142:143], v[34:35]
	v_add_f32_e32 v28, v28, v29
	s_waitcnt lgkmcnt(2)
	v_pk_mul_f32 v[108:109], v[162:163], v[156:157] op_sel_hi:[1,0]
	v_add_f32_e32 v28, v28, v30
	v_pk_fma_f32 v[20:21], v[32:33], v[148:149], v[108:109]
	s_waitcnt lgkmcnt(1)
	v_pk_mul_f32 v[32:33], v[166:167], v[26:27]
	v_add_f32_e32 v28, v28, v31
	v_add_f32_e32 v28, v28, v32
	v_pk_mul_f32 v[42:43], v[168:169], v[24:25]
	v_add_f32_e32 v28, v28, v33
	v_add_f32_e32 v28, v28, v42
	v_add_f32_e32 v30, v28, v43
	s_waitcnt lgkmcnt(0)
	v_pk_mul_f32 v[28:29], v[170:171], v[20:21]
	s_nop 0
	v_add_f32_e32 v28, v30, v28
	v_add_f32_e32 v30, v28, v29
	v_pk_mul_f32 v[28:29], v[164:165], v[156:157] op_sel_hi:[1,0]
	s_nop 0
	v_pk_fma_f32 v[22:23], v[22:23], v[150:151], v[28:29]
	s_nop 0
	v_pk_mul_f32 v[28:29], v[172:173], v[22:23]
	s_nop 0
	v_add_f32_e32 v28, v30, v28
	v_add_f32_e32 v28, v28, v29
	ds_write_b32 v160, v28 offset:6144
	s_waitcnt lgkmcnt(0)
	s_barrier
	s_and_saveexec_b64 s[22:23], s[2:3]
	s_cbranch_execz .LBB0_1681
	ds_read2st64_b32 v[28:29], v160 offset0:26 offset1:28
	ds_read_b32 v30, v3 offset:6144
	ds_read_b32 v31, v160 offset:7680
	s_waitcnt lgkmcnt(0)
	v_pk_add_f32 v[28:29], v[28:29], v[30:31]
	s_nop 0
	v_add_f32_e32 v28, v28, v29
	ds_write_b32 v160, v28 offset:9728
